# attention loop rewritten: LDS fragment prefetch ring, no S copy, permlane max exchange, V row permutation in LDS, XCD-aware unit order, half-workgroup stagger
# speedup vs baseline: 1.0083x; 1.0083x over previous
; __device__ __forceinline__ float wave_sum(float v) {
; #pragma unroll
;     for (int o = 1; o < 64; o <<= 1) v += __shfl_xor(v, o);
;     return v;
; }
; __device__ __forceinline__ void phase_attn(const PT& p, LAS unsigned char* lds, int tid, int lane, int wave) {
;     const float s1 = wave_sum(p.in[16][lane] * p.in[17][lane]), s2 = wave_sum(p.in[18][lane] * p.in[19][lane]);
;     const float lam = __expf(s1) - __expf(s2) + LAMBDA_INIT;
.LBB0_1069:
	s_or_b64 exec, exec, s[0:1]
	s_waitcnt lgkmcnt(0)
	v_mov_b32_e32 v0, 0x23eb8
	s_barrier
	ds_read_b64 v[2:3], v0
	v_mov_b32_e32 v0, 0x23ec0
	ds_read_b64 v[6:7], v0
	v_mov_b32_e32 v0, v196
	v_mov_b32_e32 v1, 0x23e80
	ds_read_b64 v[4:5], v1
	v_mov_b32_e32 v8, 0x23e90
	v_mov_b32_e32 v10, 0x23e98
	ds_read_b64 v[8:9], v8
	ds_read_b64 v[10:11], v10
	s_waitcnt lgkmcnt(2)
	v_readfirstlane_b32 s0, v4
	v_mov_b32_e32 v4, 0x23e88
	v_readfirstlane_b32 s1, v5
	ds_read_b64 v[4:5], v4
	v_and_b32_e32 v198, 63, v0
	v_lshlrev_b32_e32 v1, 2, v198
	s_waitcnt lgkmcnt(2)
	v_readfirstlane_b32 s5, v9
	v_readfirstlane_b32 s4, v8
	s_waitcnt lgkmcnt(0)
	v_readfirstlane_b32 s3, v5
	v_readfirstlane_b32 s2, v4
	v_readfirstlane_b32 s7, v11
	v_readfirstlane_b32 s6, v10
	global_load_dword v4, v1, s[0:1]
	s_nop 1
	global_load_dword v5, v1, s[2:3]
	global_load_dword v8, v1, s[4:5]
	global_load_dword v9, v1, s[6:7]
	v_mbcnt_hi_u32_b32 v1, -1, v182
	v_and_b32_e32 v10, 64, v1
	v_xor_b32_e32 v11, 1, v1
	v_add_u32_e32 v10, 64, v10
	v_cmp_lt_i32_e32 vcc, v11, v10
	v_xor_b32_e32 v12, 2, v1
	v_xor_b32_e32 v13, 4, v1
	v_cndmask_b32_e32 v11, v1, v11, vcc
	v_lshlrev_b32_e32 v11, 2, v11
	v_cmp_lt_i32_e32 vcc, v12, v10
	v_xor_b32_e32 v14, 8, v1
	v_xor_b32_e32 v15, 16, v1
	v_cndmask_b32_e32 v12, v1, v12, vcc
	v_lshlrev_b32_e32 v12, 2, v12
	v_cmp_lt_i32_e32 vcc, v13, v10
	v_xor_b32_e32 v16, 32, v1
	v_readfirstlane_b32 s2, v2
	v_cndmask_b32_e32 v13, v1, v13, vcc
	v_cmp_lt_i32_e32 vcc, v14, v10
	v_readfirstlane_b32 s3, v3
	v_readfirstlane_b32 s0, v7
	v_readfirstlane_b32 s1, v6
	s_cmpk_gt_i32 s90, 0x3ff
	v_readfirstlane_b32 s4, v0
	s_waitcnt vmcnt(2)
	v_mul_f32_e32 v17, v4, v5
	ds_bpermute_b32 v17, v11, v17
	s_waitcnt vmcnt(0)
	v_mul_f32_e32 v18, v8, v9
	ds_bpermute_b32 v11, v11, v18
	s_waitcnt lgkmcnt(1)
	v_fmac_f32_e32 v17, v4, v5
	ds_bpermute_b32 v4, v12, v17
	s_waitcnt lgkmcnt(1)
	v_fmac_f32_e32 v11, v8, v9
	ds_bpermute_b32 v5, v12, v11
	v_lshlrev_b32_e32 v9, 2, v13
	v_cndmask_b32_e32 v8, v1, v14, vcc
	s_waitcnt lgkmcnt(1)
	v_add_f32_e32 v4, v17, v4
	v_lshlrev_b32_e32 v8, 2, v8
	s_waitcnt lgkmcnt(0)
	v_add_f32_e32 v5, v11, v5
	ds_bpermute_b32 v11, v9, v4
	ds_bpermute_b32 v9, v9, v5
	v_cmp_lt_i32_e32 vcc, v15, v10
	s_waitcnt lgkmcnt(1)
	v_add_f32_e32 v4, v4, v11
	s_waitcnt lgkmcnt(0)
	v_add_f32_e32 v5, v5, v9
	ds_bpermute_b32 v9, v8, v4
	ds_bpermute_b32 v8, v8, v5
	v_cndmask_b32_e32 v12, v1, v15, vcc
	v_lshlrev_b32_e32 v179, 2, v12
	v_cmp_lt_i32_e32 vcc, v16, v10
	s_waitcnt lgkmcnt(1)
	v_add_f32_e32 v4, v4, v9
	s_waitcnt lgkmcnt(0)
	v_add_f32_e32 v5, v5, v8
	ds_bpermute_b32 v8, v179, v4
	ds_bpermute_b32 v9, v179, v5
	v_cndmask_b32_e32 v1, v1, v16, vcc
	v_lshlrev_b32_e32 v197, 2, v1
	s_waitcnt lgkmcnt(1)
	v_add_f32_e32 v1, v4, v8
	s_waitcnt lgkmcnt(0)
	v_add_f32_e32 v2, v5, v9
	ds_bpermute_b32 v3, v197, v1
	ds_bpermute_b32 v4, v197, v2
	s_cbranch_scc1 .LBB0_1111
; #define LAS __attribute__((address_space(3)))
; __device__ __forceinline__ float fexp2(float x) { return __builtin_amdgcn_exp2f(x); }
; #define PREFETCH(t) do { \
;         _Pragma("unroll") for (int i_ = 0; i_ < 4; ++i_) { const int pid_ = tid + 512 * i_, row_ = pid_ >> 4, c16_ = pid_ & 15; const unsigned go_ = (tokb + (unsigned)((t) * 128 + row_)) * 2048u + (unsigned)(hd * 128 + 8 * c16_); \
;             preK[i_] = *(const u32x4*)(Kb + go_); preV[i_] = *(const u32x4*)(Vb + go_); } \
;     } while (0)
; __device__ __forceinline__ void attn_unit(const PT& p, LAS unsigned char* lds, int tid, int lane, int wave, int b, int hd, int qb, float lam) {
;     ...
;     const int r32 = lane & 31, h = lane >> 5, mp = wave >> 2, wq = wave & 3;
;     const int qw0 = qb * 128 + 32 * wq, q = qw0 + r32; const unsigned tokq = (unsigned)(b * SEQ + q), tokb = (unsigned)(b * SEQ);
;     const float slope2 = fexp2(-0.5f * (float)(hd + 1)) * LOG2E;
;     bf16x8 qf[4];
; #pragma unroll
;     for (int ds = 0; ds < 4; ++ds) qf[ds] = ld_frag16(Qb + (tokq * 2048u + (unsigned)(hd * 128 + mp * 64 + 16 * ds + 8 * h)));
;     float mrun = -INFINITY, lsum = 0.f;
;     f32x16 oT[4];
; #pragma unroll
;     for (int db = 0; db < 4; ++db)
; #pragma unroll
;         for (int i = 0; i < 16; ++i) oT[db][i] = 0.f;
;     const int ntiles = qb + 1;
;     u32x4 preV[4], preK[4];
;     ...
;     PREFETCH(0);
;     const LAS unsigned char* kbase0 = lds + A_KOFF + r32 * AK_PITCH + (mp * 64 + 8 * h) * 2;
;     const LAS unsigned char* vbase0 = lds + A_VOFF + (4 * h + ((lane & 15) >> 2)) * AV_PITCH + ((lane >> 4) & 1) * 32 + (lane & 3) * 8;
; __device__ __forceinline__ void phase_attn(const PT& p, LAS unsigned char* lds, int tid, int lane, int wave) {
;     ...
;     const float lam = __expf(s1) - __expf(s2) + LAMBDA_INIT;
; #pragma unroll 1
;     for (int u = blockIdx.x; u < NBATCH * 16 * 8; u += gridDim.x) {
;         const int j = u & 7, hd = (u >> 3) & 15, b = u >> 7;
; #pragma unroll 1
;         for (int k = 0; k < 2; ++k) attn_unit(p, lds, tid, lane, wave, b, hd, k == 0 ? 15 - j : j, lam);
	s_waitcnt lgkmcnt(1)
	v_add_f32_e32 v1, v1, v3
	s_waitcnt lgkmcnt(0)
	v_add_f32_e32 v2, v2, v4
	v_mul_f32_e32 v1, 0x3fb8aa3b, v1
	v_mul_f32_e32 v2, 0x3fb8aa3b, v2
	v_exp_f32_e32 v1, v1
	v_exp_f32_e32 v2, v2
	s_ashr_i32 s36, s4, 6
	s_add_u32 s40, s1, 0x6900000
	s_addc_u32 s41, s0, 0
	v_sub_f32_e32 v1, v1, v2
	s_add_u32 s42, s1, 0x1a900000
	v_lshrrev_b32_e32 v2, 5, v198
	s_addc_u32 s43, s0, 0
	s_ashr_i32 s37, s4, 8
	v_lshlrev_b32_e32 v3, 3, v2
	s_and_b32 s38, s36, 3
	v_lshl_or_b32 v200, s37, 6, v3
	v_lshlrev_b32_e32 v3, 3, v0
	s_add_u32 s44, s1, 0xe900000
	v_and_b32_e32 v201, 0x78, v3
	v_add_u32_e32 v3, 0x200, v0
	s_addc_u32 s45, s0, 0
	v_lshrrev_b32_e32 v203, 4, v3
	v_add_u32_e32 v3, 0x400, v0
	v_add_f32_e32 v199, 0x3eb60549, v1
	v_and_b32_e32 v1, 31, v0
	s_add_u32 s46, s1, 0xa900000
	v_lshrrev_b32_e32 v202, 4, v0
	v_lshrrev_b32_e32 v204, 4, v3
	v_add_u32_e32 v3, 0x600, v0
	v_lshrrev_b32_e32 v4, 2, v0
	v_lshlrev_b32_e32 v0, 4, v0
	s_addc_u32 s47, s0, 0
	s_lshl_b32 s1, s37, 7
	v_lshlrev_b32_e32 v178, 2, v2
	v_and_b32_e32 v0, 0xf0, v0
	v_lshrrev_b32_e32 v205, 4, v3
	s_movk_i32 s0, 0x110
	v_mul_u32_u24_e32 v3, 0x110, v1
	s_add_i32 s1, s1, 0
	v_and_b32_e32 v4, 3, v4
	v_lshl_or_b32 v4, v4, 2, v2
	v_lshlrev_b32_e32 v5, 1, v198
	v_lshlrev_b32_e32 v6, 3, v198
	v_add_u32_e32 v206, 0, v0
	v_lshlrev_b32_e32 v0, 4, v2
	v_and_b32_e32 v5, 32, v5
	v_and_b32_e32 v6, 24, v6
	v_add3_u32 v211, s1, v3, v0
	v_mad_u32_u24 v0, v4, s0, 0
	v_add3_u32 v212, v0, v5, v6
	v_or_b32_e32 v0, 2, v178
	v_cmp_gt_u32_e64 s[6:7], v0, v1
	v_or_b32_e32 v0, 3, v178
	v_cmp_gt_u32_e64 s[8:9], v0, v1
	v_or_b32_e32 v0, 9, v178
	v_cmp_gt_u32_e64 s[12:13], v0, v1
	v_or_b32_e32 v0, 10, v178
	v_cmp_gt_u32_e64 s[14:15], v0, v1
	v_or_b32_e32 v0, 11, v178
	v_cmp_gt_u32_e64 s[16:17], v0, v1
	v_or_b32_e32 v0, 17, v178
	v_cmp_gt_u32_e64 s[20:21], v0, v1
	v_or_b32_e32 v0, 18, v178
	s_cmp_lg_u32 s38, 0
	v_cmp_gt_u32_e64 s[22:23], v0, v1
	v_or_b32_e32 v0, 19, v178
	s_cselect_b64 s[48:49], -1, 0
	s_cmp_eq_u32 s38, 0
	v_cmp_gt_u32_e64 s[24:25], v0, v1
	v_or_b32_e32 v0, 25, v178
	s_cselect_b64 s[50:51], -1, 0
	v_cmp_gt_u32_e64 s[28:29], v0, v1
	v_or_b32_e32 v0, 26, v178
	s_cmp_eq_u32 s38, 1
	v_cmp_gt_u32_e64 s[30:31], v0, v1
	v_or_b32_e32 v0, 27, v178
	s_cselect_b64 s[52:53], -1, 0
	s_cmp_eq_u32 s38, 2
	v_cmp_gt_u32_e64 s[34:35], v0, v1
	v_sub_u32_e64 v0, s38, 1 clamp
	s_cselect_b64 s[54:55], -1, 0
	s_cmp_eq_u32 s38, 3
	v_readfirstlane_b32 s33, v0
	s_cselect_b64 s[56:57], -1, 0
	s_lshl_b32 s39, s38, 14
	v_lshl_or_b32 v0, v205, 11, v201
	v_writelane_b32 v249, s70, 41
	s_add_i32 s86, s39, 0
	v_add_u32_e32 v229, 0x40000, v0
	v_lshl_or_b32 v0, v204, 11, v201
	v_writelane_b32 v249, s71, 42
	s_cmp_eq_u32 s37, 1
	v_add_u32_e32 v230, 0x40000, v0
	v_lshl_or_b32 v0, v203, 11, v201
	v_or_b32_e32 v213, 8, v178
	v_or_b32_e32 v214, 16, v178
	v_or_b32_e32 v215, 24, v178
	s_cselect_b64 s[58:59], -1, 0
	s_cmp_lt_u32 s36, 4
	v_readlane_b32 s36, v249, 0
	v_add_u32_e32 v231, 0x40000, v0
	v_lshl_or_b32 v0, v202, 11, v201
	s_mov_b32 s62, 2.0
	s_mov_b32 s64, 0x41000000
	s_mov_b32 s66, 0x41200000
	s_mov_b32 s68, 0x41800000
	s_mov_b32 s70, 0x41900000
	s_mov_b32 s72, 0x41c00000
	s_mov_b32 s74, 0x41d00000
	v_mul_lo_u32 v207, v202, s0
	v_mul_lo_u32 v208, v203, s0
	v_mul_lo_u32 v209, v204, s0
	v_mul_lo_u32 v210, v205, s0
	v_cmp_gt_u32_e64 s[0:1], v178, v1
	v_cmp_lt_u32_e64 s[4:5], v178, v1
	v_cmp_gt_u32_e64 s[10:11], v213, v1
	v_cmp_gt_u32_e64 s[18:19], v214, v1
	v_cmp_gt_u32_e64 s[26:27], v215, v1
	s_cselect_b64 s[60:61], -1, 0
	v_mov_b32_e32 v51, 0
	v_or_b32_e32 v216, 32, v178
	v_or_b32_e32 v217, 40, v178
	v_or_b32_e32 v218, 48, v178
	v_or_b32_e32 v219, 56, v178
	v_or_b32_e32 v220, 64, v178
	v_or_b32_e32 v221, 0x48, v178
	v_or_b32_e32 v222, 0x50, v178
	v_or_b32_e32 v223, 0x58, v178
	v_or_b32_e32 v224, 0x60, v178
	v_or_b32_e32 v225, 0x68, v178
	v_or_b32_e32 v226, 0x70, v178
	v_or_b32_e32 v227, 0x78, v178
	v_lshl_or_b32 v228, s38, 5, v1
	s_lshl_b32 s38, s90, 4
	s_lshl_b32 s36, s36, 4
	v_add_u32_e32 v232, 0x40000, v0
	s_mov_b32 s63, 0x40400000
	s_mov_b32 s65, 0x41100000
	s_mov_b32 s67, 0x41300000
	s_mov_b32 s69, 0x41880000
	s_mov_b32 s71, 0x41980000
	s_mov_b32 s73, 0x41c80000
	s_mov_b32 s75, 0x41d80000
	s_mov_b32 s89, 0xff800000
	v_mov_b32_e32 v233, 0x23ea0
	v_mov_b32_e32 v234, 0x3727c5ac
	v_mov_b32_e32 v16, 0xff800000
	v_readlane_b32 s37, v249, 1
	v_writelane_b32 v249, s36, 39
	s_branch .LBB0_1072

; __device__ __forceinline__ float fexp2(float x) { return __builtin_amdgcn_exp2f(x); }
; #define PREFETCH(t) do { \
;         _Pragma("unroll") for (int i_ = 0; i_ < 4; ++i_) { const int pid_ = tid + 512 * i_, row_ = pid_ >> 4, c16_ = pid_ & 15; const unsigned go_ = (tokb + (unsigned)((t) * 128 + row_)) * 2048u + (unsigned)(hd * 128 + 8 * c16_); \
;             preK[i_] = *(const u32x4*)(Kb + go_); preV[i_] = *(const u32x4*)(Vb + go_); } \
;     } while (0)
; __device__ __forceinline__ void attn_unit(const PT& p, LAS unsigned char* lds, int tid, int lane, int wave, int b, int hd, int qb, float lam) {
;     ...
;     const int qw0 = qb * 128 + 32 * wq, q = qw0 + r32; const unsigned tokq = (unsigned)(b * SEQ + q), tokb = (unsigned)(b * SEQ);
;     const float slope2 = fexp2(-0.5f * (float)(hd + 1)) * LOG2E;
;     bf16x8 qf[4];
; #pragma unroll
;     for (int ds = 0; ds < 4; ++ds) qf[ds] = ld_frag16(Qb + (tokq * 2048u + (unsigned)(hd * 128 + mp * 64 + 16 * ds + 8 * h)));
;     float mrun = -INFINITY, lsum = 0.f;
;     f32x16 oT[4];
; #pragma unroll
;     for (int db = 0; db < 4; ++db)
; #pragma unroll
;         for (int i = 0; i < 16; ++i) oT[db][i] = 0.f;
;     const int ntiles = qb + 1;
;     u32x4 preV[4], preK[4];
;     ...
;     PREFETCH(0);
; __device__ __forceinline__ void phase_attn(const PT& p, LAS unsigned char* lds, int tid, int lane, int wave) {
;     ...
;     for (int u = blockIdx.x; u < NBATCH * 16 * 8; u += gridDim.x) {
;         const int j = u & 7, hd = (u >> 3) & 15, b = u >> 7;
; #pragma unroll 1
;         for (int k = 0; k < 2; ++k) attn_unit(p, lds, tid, lane, wave, b, hd, k == 0 ? 15 - j : j, lam);
.LBB0_1072:
	s_and_b32 s98, s90, 0xffffffc0
	s_bfe_u32 s99, s90, 0x30003
	s_or_b32 s98, s98, s99
	s_and_b32 s99, s90, 7
	s_lshl_b32 s99, s99, 3
	s_or_b32 s98, s98, s99
	s_lshl_b32 s36, s98, 15
	s_bfe_u32 s37, s98, 0x40003
	s_and_b32 s36, s36, 0xffc00000
	s_lshl_b32 s91, s37, 7
	s_or_b32 s36, s91, s36
	s_add_i32 s37, s37, 1
	v_add_u32_e32 v235, s36, v229
	v_add_u32_e32 v236, s36, v230
	v_add_u32_e32 v237, s36, v231
	v_add_u32_e32 v238, s36, v232
	s_lshl_b32 s36, s98, 4
	v_cvt_f32_ubyte0_e32 v0, s37
	s_and_b32 s94, s36, 0xfffff800
	v_mul_f32_e32 v0, -0.5, v0
	v_exp_f32_e32 v2, v0
	v_or_b32_e32 v3, s91, v201
	v_add_u32_e32 v0, s94, v202
	v_lshl_or_b32 v50, v0, 11, v3
	v_lshlrev_b64 v[0:1], 1, v[50:51]
	v_lshl_add_u64 v[180:181], s[46:47], 0, v[0:1]
	v_lshl_add_u64 v[182:183], s[42:43], 0, v[0:1]
	v_add_u32_e32 v0, s94, v203
	v_lshl_or_b32 v50, v0, 11, v3
	v_lshlrev_b64 v[0:1], 1, v[50:51]
	v_lshl_add_u64 v[184:185], s[46:47], 0, v[0:1]
	v_lshl_add_u64 v[186:187], s[42:43], 0, v[0:1]
	v_add_u32_e32 v0, s94, v204
	v_lshl_or_b32 v50, v0, 11, v3
	v_lshlrev_b64 v[0:1], 1, v[50:51]
	v_lshl_add_u64 v[188:189], s[46:47], 0, v[0:1]
	v_lshl_add_u64 v[190:191], s[42:43], 0, v[0:1]
	v_add_u32_e32 v0, s94, v205
	v_lshl_or_b32 v50, v0, 11, v3
	s_and_b32 s92, s98, 7
	v_lshlrev_b64 v[0:1], 1, v[50:51]
	s_xor_b32 s93, s92, 15
	v_add_u32_e32 v239, s91, v200
	v_lshl_add_u64 v[192:193], s[46:47], 0, v[0:1]
	v_lshl_add_u64 v[194:195], s[42:43], 0, v[0:1]
	v_mul_f32_e32 v240, 0x3fb8aa3b, v2
	s_mov_b64 s[36:37], -1
	v_writelane_b32 v249, s38, 37
	s_branch .LBB0_1074

; #define LAS __attribute__((address_space(3)))
; __device__ __forceinline__ float fexp2(float x) { return __builtin_amdgcn_exp2f(x); }
; #define PREFETCH(t) do { \
;         _Pragma("unroll") for (int i_ = 0; i_ < 4; ++i_) { const int pid_ = tid + 512 * i_, row_ = pid_ >> 4, c16_ = pid_ & 15; const unsigned go_ = (tokb + (unsigned)((t) * 128 + row_)) * 2048u + (unsigned)(hd * 128 + 8 * c16_); \
;             preK[i_] = *(const u32x4*)(Kb + go_); preV[i_] = *(const u32x4*)(Vb + go_); } \
;     } while (0)
; #define STAGE_WRITE(stg) do { \
;         _Pragma("unroll") for (int i_ = 0; i_ < 4; ++i_) { const int pid_ = tid + 512 * i_, row_ = pid_ >> 4, c16_ = pid_ & 15; \
;             *(LAS u32x4*)(lds + (stg) * A_STAGE + A_KOFF + row_ * AK_PITCH + 16 * c16_) = preK[i_]; *(LAS u32x4*)(lds + (stg) * A_STAGE + A_VOFF + row_ * AV_PITCH + 16 * c16_) = preV[i_]; } \
;     } while (0)
; __device__ __forceinline__ void attn_unit(const PT& p, LAS unsigned char* lds, int tid, int lane, int wave, int b, int hd, int qb, float lam) {
;     ...
;     const int qw0 = qb * 128 + 32 * wq, q = qw0 + r32; const unsigned tokq = (unsigned)(b * SEQ + q), tokb = (unsigned)(b * SEQ);
;     const float slope2 = fexp2(-0.5f * (float)(hd + 1)) * LOG2E;
;     bf16x8 qf[4];
; #pragma unroll
;     for (int ds = 0; ds < 4; ++ds) qf[ds] = ld_frag16(Qb + (tokq * 2048u + (unsigned)(hd * 128 + mp * 64 + 16 * ds + 8 * h)));
;     float mrun = -INFINITY, lsum = 0.f;
;     f32x16 oT[4];
; #pragma unroll
;     for (int db = 0; db < 4; ++db)
; #pragma unroll
;         for (int i = 0; i < 16; ++i) oT[db][i] = 0.f;
;     const int ntiles = qb + 1;
;     u32x4 preV[4], preK[4];
;     ...
;     PREFETCH(0);
;     const LAS unsigned char* kbase0 = lds + A_KOFF + r32 * AK_PITCH + (mp * 64 + 8 * h) * 2;
;     const LAS unsigned char* vbase0 = lds + A_VOFF + (4 * h + ((lane & 15) >> 2)) * AV_PITCH + ((lane >> 4) & 1) * 32 + (lane & 3) * 8;
;     ...
;     __syncthreads();
;     STAGE_WRITE(0);
;     asm volatile("" : "+v"(qf[0]), "+v"(qf[1]), "+v"(qf[2]), "+v"(qf[3]));
;     __syncthreads();
.LBB0_1074:
	s_xor_b64 s[76:77], s[36:37], -1
	s_and_b64 s[36:37], s[36:37], exec
	s_cselect_b32 s95, s93, s92
	v_lshl_or_b32 v8, s95, 7, v228
	v_or_b32_e32 v0, s94, v8
	v_lshlrev_b32_e32 v241, 11, v0
	v_add_u32_e32 v50, v239, v241
	v_lshl_add_u64 v[0:1], v[50:51], 1, s[40:41]
	v_or_b32_e32 v2, 16, v50
	v_mov_b32_e32 v3, v51
	v_or_b32_e32 v4, 32, v50
	v_mov_b32_e32 v5, v51
	v_or_b32_e32 v50, 48, v50
	v_lshl_add_u64 v[2:3], v[2:3], 1, s[40:41]
	v_lshl_add_u64 v[4:5], v[4:5], 1, s[40:41]
	v_lshl_add_u64 v[6:7], v[50:51], 1, s[40:41]
	global_load_dwordx4 v[134:137], v[180:181], off
	global_load_dwordx4 v[138:141], v[182:183], off
	global_load_dwordx4 v[154:157], v[184:185], off
	global_load_dwordx4 v[158:161], v[186:187], off
	global_load_dwordx4 v[162:165], v[188:189], off
	global_load_dwordx4 v[166:169], v[190:191], off
	global_load_dwordx4 v[170:173], v[192:193], off
	global_load_dwordx4 v[174:177], v[194:195], off
	global_load_dwordx4 v[130:133], v[0:1], off
	global_load_dwordx4 v[142:145], v[6:7], off
	global_load_dwordx4 v[146:149], v[4:5], off
	global_load_dwordx4 v[150:153], v[2:3], off
	v_add_u32_e32 v0, v206, v207
	s_barrier
	v_mov_b32_e32 v64, v51
	v_mov_b32_e32 v65, v51
	s_lshl_b32 s96, s95, 18
	v_mov_b32_e32 v50, v51
	v_mov_b32_e32 v52, v51
	v_mov_b32_e32 v53, v51
	v_mov_b32_e32 v54, v51
	v_mov_b32_e32 v55, v51
	v_mov_b32_e32 v56, v51
	v_mov_b32_e32 v57, v51
	v_mov_b32_e32 v58, v51
	v_mov_b32_e32 v59, v51
	v_mov_b32_e32 v60, v51
	v_mov_b32_e32 v61, v51
	v_mov_b32_e32 v62, v51
	v_mov_b32_e32 v63, v51
	v_mov_b64_e32 v[80:81], v[64:65]
	v_mov_b64_e32 v[96:97], v[64:65]
	v_mov_b64_e32 v[112:113], v[64:65]
	v_mov_b64_e32 v[128:129], v[64:65]
	v_sub_u32_e32 v242, v178, v8
	s_add_i32 s97, s96, 0x40000
	s_mov_b32 s38, 0
	v_mov_b32_e32 v248, 0xff800000
	v_mov_b32_e32 v243, 0
	v_mov_b64_e32 v[78:79], v[62:63]
	v_mov_b64_e32 v[76:77], v[60:61]
	v_mov_b64_e32 v[74:75], v[58:59]
	v_mov_b64_e32 v[72:73], v[56:57]
	v_mov_b64_e32 v[70:71], v[54:55]
	v_mov_b64_e32 v[68:69], v[52:53]
	v_mov_b64_e32 v[66:67], v[50:51]
	v_mov_b64_e32 v[94:95], v[62:63]
	v_mov_b64_e32 v[92:93], v[60:61]
	v_mov_b64_e32 v[90:91], v[58:59]
	v_mov_b64_e32 v[88:89], v[56:57]
	v_mov_b64_e32 v[86:87], v[54:55]
	v_mov_b64_e32 v[84:85], v[52:53]
	v_mov_b64_e32 v[82:83], v[50:51]
	v_mov_b64_e32 v[110:111], v[62:63]
	v_mov_b64_e32 v[108:109], v[60:61]
	v_mov_b64_e32 v[106:107], v[58:59]
	v_mov_b64_e32 v[104:105], v[56:57]
	v_mov_b64_e32 v[102:103], v[54:55]
	v_mov_b64_e32 v[100:101], v[52:53]
	v_mov_b64_e32 v[98:99], v[50:51]
	v_mov_b64_e32 v[126:127], v[62:63]
	v_mov_b64_e32 v[124:125], v[60:61]
	v_mov_b64_e32 v[122:123], v[58:59]
	v_mov_b64_e32 v[120:121], v[56:57]
	v_mov_b64_e32 v[118:119], v[54:55]
	v_mov_b64_e32 v[116:117], v[52:53]
	v_mov_b64_e32 v[114:115], v[50:51]
	s_mov_b32 s39, 0
	s_waitcnt vmcnt(11)
	ds_write_b128 v0, v[134:137]
	s_waitcnt vmcnt(10)
	v_bfe_u32 v2, v196, 4, 2
	v_bfe_u32 v3, v196, 6, 2
	v_sub_u32_e32 v2, v2, v3
	v_mul_i32_i24_e32 v2, 0x330, v2
	v_add_u32_e32 v3, v2, v0
	ds_write_b128 v3, v[138:141] offset:34816
	v_add_u32_e32 v0, v206, v208
	s_waitcnt vmcnt(9)
	ds_write_b128 v0, v[154:157]
	s_waitcnt vmcnt(8)
	v_add_u32_e32 v3, v2, v0
	ds_write_b128 v3, v[158:161] offset:34816
	v_add_u32_e32 v0, v206, v209
	s_waitcnt vmcnt(7)
	ds_write_b128 v0, v[162:165]
	s_waitcnt vmcnt(6)
	v_add_u32_e32 v3, v2, v0
	ds_write_b128 v3, v[166:169] offset:34816
	v_add_u32_e32 v0, v206, v210
	s_waitcnt vmcnt(5)
	ds_write_b128 v0, v[170:173]
	s_waitcnt vmcnt(4)
	v_add_u32_e32 v3, v2, v0
	ds_write_b128 v3, v[174:177] offset:34816
	s_waitcnt vmcnt(0)
	s_waitcnt lgkmcnt(0)
	s_barrier
	s_branch .LBB0_1076

; #define LAS __attribute__((address_space(3)))
; __device__ __forceinline__ int crow(int r, int h) { return (r & 3) + 8 * (r >> 2) + 4 * h; }
; __device__ __forceinline__ f32x16 mfma32(bf16x8 a, bf16x8 b, f32x16 c) { return __builtin_amdgcn_mfma_f32_32x32x16_bf16(a, b, c, 0, 0, 0); }
; __device__ __forceinline__ void attn_unit(const PT& p, LAS unsigned char* lds, int tid, int lane, int wave, int b, int hd, int qb, float lam) {
;     ...
;         for (int sub = 0; sub < 2; ++sub) {
;             const int nact = diag ? min(2, max(0, wq + 1 - 2 * sub)) : 2;
;             if (nact > 0) {
;                 float sl = slope2; asm volatile("" : "+v"(sl));
;                 const float bq = sl * (float)(t * 128 + sub * 64 + 4 * h - q);
;                 const LAS unsigned char* kb0 = kbase + sub * 64 * AK_PITCH; const LAS unsigned char* vb0 = vbase + sub * 64 * AV_PITCH;
;                 f32x16 s[2];
; #pragma unroll
;                 for (int kb = 0; kb < 2; ++kb) {
;                     if (kb < nact) {
;                         const float bk = bq + sl * (float)(32 * kb);
; #pragma unroll
;                         for (int i = 0; i < 16; ++i) s[kb][i] = __builtin_fmaf(sl, (float)((i & 3) + 8 * (i >> 2)), bk);
; #pragma unroll
;                         for (int ds = 0; ds < 4; ++ds) s[kb] = mfma32(__builtin_bit_cast(bf16x8, *(const LAS u32x4*)(kb0 + kb * 32 * AK_PITCH + ds * 32)), qf[ds], s[kb]);
;                     } else {
; #pragma unroll
;                         for (int i = 0; i < 16; ++i) s[kb][i] = -INFINITY;
;                     }
;                 }
;                 if (diag) {
; #pragma unroll
;                     for (int kb = 0; kb < 2; ++kb) if (2 * sub + kb == wq) {
; #pragma unroll
;                         for (int i = 0; i < 16; ++i) if (crow(i, h) > r32) s[kb][i] = -INFINITY; }
;                 }
.LBB0_1078:
	s_and_b32 s87, s39, 1
	s_mul_i32 s88, s87, 0x11000
	v_add_u32_e32 v56, s88, v211
	s_add_i32 s36, s88, 0x8800
	v_add_u32_e32 v254, s36, v212
	s_cmp_lg_u32 s96, s38
	s_cselect_b64 s[82:83], -1, 0
	s_cmp_eq_u32 s96, s38
	s_cselect_b64 s[80:81], -1, 0
	s_or_b64 s[84:85], s[48:49], s[82:83]
	s_and_b64 vcc, exec, s[58:59]
	s_cbranch_vccz .Lat_nostagger
	s_sleep 12
.Lat_nostagger:
	ds_read_b128 v[0:3], v56 offset:0
	ds_read_b128 v[4:7], v56 offset:32
	ds_read_b128 v[8:11], v56 offset:64
	ds_read_b128 v[12:15], v56 offset:96
	v_cvt_f32_i32_e32 v50, v242
	v_mul_f32_e32 v255, v240, v50
	v_mov_b32_e32 v18, v255
	v_add_f32_e32 v19, v240, v255
	v_fma_f32 v20, v240, s62, v255
	v_fma_f32 v21, v240, s63, v255
	v_fma_f32 v22, v240, s64, v255
	v_fma_f32 v23, v240, s65, v255
	v_fma_f32 v24, v240, s66, v255
	v_fma_f32 v25, v240, s67, v255
	v_fma_f32 v26, v240, s68, v255
	v_fma_f32 v27, v240, s69, v255
	v_fma_f32 v28, v240, s70, v255
	v_fma_f32 v29, v240, s71, v255
	v_fma_f32 v30, v240, s72, v255
	v_fma_f32 v31, v240, s73, v255
	v_fma_f32 v32, v240, s74, v255
	v_fma_f32 v33, v240, s75, v255
	s_andn2_b64 vcc, exec, s[84:85]
	s_cbranch_vccnz .Lat0_k1off
	ds_read_b128 v[250:253], v56 offset:8704
	ds_read_b128 v[244:247], v56 offset:8736
	s_waitcnt lgkmcnt(5)
	v_mfma_f32_32x32x16_bf16 v[18:33], v[0:3], v[130:133], v[18:33]
	ds_read_b128 v[0:3], v56 offset:8768
	v_fmac_f32_e32 v255, 0x42000000, v240
	v_mov_b32_e32 v34, v255
	v_add_f32_e32 v35, v240, v255
	v_fma_f32 v36, v240, s62, v255
	v_fma_f32 v37, v240, s63, v255
	v_fma_f32 v38, v240, s64, v255
	s_waitcnt lgkmcnt(5)
	v_mfma_f32_32x32x16_bf16 v[18:33], v[4:7], v[150:153], v[18:33]
	ds_read_b128 v[4:7], v56 offset:8800
	v_fma_f32 v39, v240, s65, v255
	v_fma_f32 v40, v240, s66, v255
	v_fma_f32 v41, v240, s67, v255
	v_fma_f32 v42, v240, s68, v255
	v_fma_f32 v43, v240, s69, v255
	v_fma_f32 v44, v240, s70, v255
	s_waitcnt lgkmcnt(5)
	v_mfma_f32_32x32x16_bf16 v[18:33], v[8:11], v[146:149], v[18:33]
	v_fma_f32 v45, v240, s71, v255
	v_fma_f32 v46, v240, s72, v255
	v_fma_f32 v47, v240, s73, v255
	v_fma_f32 v48, v240, s74, v255
	v_fma_f32 v49, v240, s75, v255
	s_waitcnt lgkmcnt(4)
	v_mfma_f32_32x32x16_bf16 v[18:33], v[12:15], v[142:145], v[18:33]
	s_waitcnt lgkmcnt(3)
	v_mfma_f32_32x32x16_bf16 v[34:49], v[250:253], v[130:133], v[34:49]
	s_waitcnt lgkmcnt(2)
	v_mfma_f32_32x32x16_bf16 v[34:49], v[244:247], v[150:153], v[34:49]
	s_waitcnt lgkmcnt(1)
	v_mfma_f32_32x32x16_bf16 v[34:49], v[0:3], v[146:149], v[34:49]
	s_waitcnt lgkmcnt(0)
	v_mfma_f32_32x32x16_bf16 v[34:49], v[4:7], v[142:145], v[34:49]
	s_branch .Lat0_qkdone
.Lat0_k1off:
	s_nop 0
	s_waitcnt lgkmcnt(3)
	v_mfma_f32_32x32x16_bf16 v[18:33], v[0:3], v[130:133], v[18:33]
	s_waitcnt lgkmcnt(2)
	v_mfma_f32_32x32x16_bf16 v[18:33], v[4:7], v[150:153], v[18:33]
	s_waitcnt lgkmcnt(1)
	v_mfma_f32_32x32x16_bf16 v[18:33], v[8:11], v[146:149], v[18:33]
	s_waitcnt lgkmcnt(0)
	v_mfma_f32_32x32x16_bf16 v[18:33], v[12:15], v[142:145], v[18:33]
	v_mov_b32_e32 v34, v16
	v_mov_b32_e32 v35, v16
	v_mov_b32_e32 v36, v16
	v_mov_b32_e32 v37, v16
	v_mov_b32_e32 v38, v16
	v_mov_b32_e32 v39, v16
	v_mov_b32_e32 v40, v16
	v_mov_b32_e32 v41, v16
	v_mov_b32_e32 v42, v16
	v_mov_b32_e32 v43, v16
	v_mov_b32_e32 v44, v16
	v_mov_b32_e32 v45, v16
	v_mov_b32_e32 v46, v16
	v_mov_b32_e32 v47, v16
	v_mov_b32_e32 v48, v16
	v_mov_b32_e32 v49, v16
.Lat0_qkdone:
	s_and_b64 vcc, exec, s[80:81]
	s_cbranch_vccz .Lat0_nodiag
	s_nop 15
	s_andn2_b64 vcc, exec, s[50:51]
	s_cbranch_vccnz .Lat0_m1
	v_cndmask_b32_e64 v18, v18, v16, s[0:1]
	v_cndmask_b32_e64 v19, v16, v19, s[4:5]
	v_cndmask_b32_e64 v20, v20, v16, s[6:7]
	v_cndmask_b32_e64 v21, v21, v16, s[8:9]
	v_cndmask_b32_e64 v22, v22, v16, s[10:11]
	v_cndmask_b32_e64 v23, v23, v16, s[12:13]
	v_cndmask_b32_e64 v24, v24, v16, s[14:15]
	v_cndmask_b32_e64 v25, v25, v16, s[16:17]
	v_cndmask_b32_e64 v26, v26, v16, s[18:19]
	v_cndmask_b32_e64 v27, v27, v16, s[20:21]
	v_cndmask_b32_e64 v28, v28, v16, s[22:23]
	v_cndmask_b32_e64 v29, v29, v16, s[24:25]
	v_cndmask_b32_e64 v30, v30, v16, s[26:27]
	v_cndmask_b32_e64 v31, v31, v16, s[28:29]
	v_cndmask_b32_e64 v32, v32, v16, s[30:31]
	v_cndmask_b32_e64 v33, v33, v16, s[34:35]
.Lat0_m1:
	s_andn2_b64 vcc, exec, s[52:53]
	s_cbranch_vccnz .Lat0_nodiag
	v_cndmask_b32_e64 v34, v34, v16, s[0:1]
	v_cndmask_b32_e64 v35, v16, v35, s[4:5]
	v_cndmask_b32_e64 v36, v36, v16, s[6:7]
	v_cndmask_b32_e64 v37, v37, v16, s[8:9]
	v_cndmask_b32_e64 v38, v38, v16, s[10:11]
	v_cndmask_b32_e64 v39, v39, v16, s[12:13]
	v_cndmask_b32_e64 v40, v40, v16, s[14:15]
	v_cndmask_b32_e64 v41, v41, v16, s[16:17]
	v_cndmask_b32_e64 v42, v42, v16, s[18:19]
	v_cndmask_b32_e64 v43, v43, v16, s[20:21]
	v_cndmask_b32_e64 v44, v44, v16, s[22:23]
	v_cndmask_b32_e64 v45, v45, v16, s[24:25]
	v_cndmask_b32_e64 v46, v46, v16, s[26:27]
	v_cndmask_b32_e64 v47, v47, v16, s[28:29]
	v_cndmask_b32_e64 v48, v48, v16, s[30:31]
	v_cndmask_b32_e64 v49, v49, v16, s[34:35]
; #define LAS __attribute__((address_space(3)))
; __device__ __forceinline__ float fexp2(float x) { return __builtin_amdgcn_exp2f(x); }
; __device__ __forceinline__ float max3f(float a, float b, float c) { return fmaxf(fmaxf(a, b), c); }
; __device__ __forceinline__ void attn_unit(const PT& p, LAS unsigned char* lds, int tid, int lane, int wave, int b, int hd, int qb, float lam) {
;     ...
;                 float mx = -INFINITY;
; #pragma unroll
;                 for (int kb = 0; kb < 2; ++kb)
; #pragma unroll
;                     for (int i = 0; i < 16; i += 2) mx = max3f(mx, s[kb][i], s[kb][i + 1]);
;                 mx = fmaxf(mx, __shfl_xor(mx, 32));
;                 const float mnew = fmaxf(mrun, mx), alpha = fexp2(mrun - mnew); mrun = mnew;
;                 float rs0 = 0.f, rs1 = 0.f, rs2 = 0.f, rs3 = 0.f;
; #pragma unroll
;                 for (int kb = 0; kb < 2; ++kb)
; #pragma unroll
;                     for (int i = 0; i < 16; i += 4) { s[kb][i] = fexp2(s[kb][i] - mnew); s[kb][i + 1] = fexp2(s[kb][i + 1] - mnew); s[kb][i + 2] = fexp2(s[kb][i + 2] - mnew); s[kb][i + 3] = fexp2(s[kb][i + 3] - mnew);
;                         rs0 += s[kb][i]; rs1 += s[kb][i + 1]; rs2 += s[kb][i + 2]; rs3 += s[kb][i + 3]; }
;                 lsum = lsum * alpha + ((rs0 + rs1) + (rs2 + rs3));
;                 if (__builtin_amdgcn_ballot_w64(alpha != 1.0f) != 0ull) {
; #pragma unroll
;                     for (int db = 0; db < 4; ++db)
; #pragma unroll
;                         for (int i = 0; i < 16; ++i) oT[db][i] *= alpha;
;                 }
; #pragma unroll
;                 for (int kb = 0; kb < 2; ++kb) if (kb < nact) {
; #pragma unroll
;                     for (int s2 = 0; s2 < 2; ++s2) {
;                         const bf16x8 pf = pack_frag(s[kb], s2);
; #pragma unroll
;                         for (int db = 0; db < 4; ++db) {
;                             const LAS unsigned char* vp = vb0 + (kb * 32 + 16 * s2) * AV_PITCH + db * 64;
;                             const v4i16_t lo = __builtin_amdgcn_ds_read_tr16_b64_v4i16((LAS v4i16_t*)vp), hi = __builtin_amdgcn_ds_read_tr16_b64_v4i16((LAS v4i16_t*)(vp + 8 * AV_PITCH));
;                             const bf16x8 vf = {lo[0], lo[1], lo[2], lo[3], hi[0], hi[1], hi[2], hi[3]};
;                             oT[db] = mfma32(vf, pf, oT[db]);
;                         }
;                     }
;                 }
.Lat0_nodiag:
	ds_read_b64_tr_b16 v[250:251], v254 offset:0
	ds_read_b64_tr_b16 v[252:253], v254 offset:544
	ds_read_b64_tr_b16 v[244:245], v254 offset:64
	ds_read_b64_tr_b16 v[246:247], v254 offset:608
	s_nop 1
	v_max3_f32 v0, v18, s89, v19
	v_max3_f32 v0, v0, v20, v21
	v_max3_f32 v0, v0, v22, v23
	v_max3_f32 v0, v0, v24, v25
	v_max3_f32 v0, v0, v26, v27
	v_max3_f32 v0, v0, v28, v29
	v_max3_f32 v0, v0, v30, v31
	v_max3_f32 v0, v0, v32, v33
	v_max3_f32 v0, v0, v34, v35
	v_max3_f32 v0, v0, v36, v37
	v_max3_f32 v0, v0, v38, v39
	v_max3_f32 v0, v0, v40, v41
	v_max3_f32 v0, v0, v42, v43
	v_max3_f32 v0, v0, v44, v45
	v_max3_f32 v0, v0, v46, v47
	v_max3_f32 v0, v0, v48, v49
	v_mov_b32_e32 v1, v0
	s_nop 1
	v_permlane32_swap_b32_e32 v0, v1
	v_max3_f32 v54, v248, v0, v1
	v_sub_f32_e32 v0, v248, v54
	v_exp_f32_e32 v0, v0
	s_nop 0
	v_cmp_neq_f32_e32 vcc, 1.0, v0
	s_cbranch_vccz .Lat0_noresc
	v_pk_mul_f32 v[128:129], v[128:129], v[0:1] op_sel_hi:[1,0]
	v_pk_mul_f32 v[126:127], v[126:127], v[0:1] op_sel_hi:[1,0]
	v_pk_mul_f32 v[124:125], v[124:125], v[0:1] op_sel_hi:[1,0]
	v_pk_mul_f32 v[122:123], v[122:123], v[0:1] op_sel_hi:[1,0]
	v_pk_mul_f32 v[120:121], v[120:121], v[0:1] op_sel_hi:[1,0]
	v_pk_mul_f32 v[118:119], v[118:119], v[0:1] op_sel_hi:[1,0]
	v_pk_mul_f32 v[116:117], v[116:117], v[0:1] op_sel_hi:[1,0]
	v_pk_mul_f32 v[114:115], v[114:115], v[0:1] op_sel_hi:[1,0]
	v_pk_mul_f32 v[112:113], v[112:113], v[0:1] op_sel_hi:[1,0]
	v_pk_mul_f32 v[110:111], v[110:111], v[0:1] op_sel_hi:[1,0]
	v_pk_mul_f32 v[108:109], v[108:109], v[0:1] op_sel_hi:[1,0]
	v_pk_mul_f32 v[106:107], v[106:107], v[0:1] op_sel_hi:[1,0]
	v_pk_mul_f32 v[104:105], v[104:105], v[0:1] op_sel_hi:[1,0]
	v_pk_mul_f32 v[102:103], v[102:103], v[0:1] op_sel_hi:[1,0]
	v_pk_mul_f32 v[100:101], v[100:101], v[0:1] op_sel_hi:[1,0]
	v_pk_mul_f32 v[98:99], v[98:99], v[0:1] op_sel_hi:[1,0]
	v_pk_mul_f32 v[96:97], v[96:97], v[0:1] op_sel_hi:[1,0]
	v_pk_mul_f32 v[94:95], v[94:95], v[0:1] op_sel_hi:[1,0]
	v_pk_mul_f32 v[92:93], v[92:93], v[0:1] op_sel_hi:[1,0]
	v_pk_mul_f32 v[90:91], v[90:91], v[0:1] op_sel_hi:[1,0]
	v_pk_mul_f32 v[88:89], v[88:89], v[0:1] op_sel_hi:[1,0]
	v_pk_mul_f32 v[86:87], v[86:87], v[0:1] op_sel_hi:[1,0]
	v_pk_mul_f32 v[84:85], v[84:85], v[0:1] op_sel_hi:[1,0]
	v_pk_mul_f32 v[82:83], v[82:83], v[0:1] op_sel_hi:[1,0]
	v_pk_mul_f32 v[80:81], v[80:81], v[0:1] op_sel_hi:[1,0]
	v_pk_mul_f32 v[78:79], v[78:79], v[0:1] op_sel_hi:[1,0]
	v_pk_mul_f32 v[76:77], v[76:77], v[0:1] op_sel_hi:[1,0]
	v_pk_mul_f32 v[74:75], v[74:75], v[0:1] op_sel_hi:[1,0]
	v_pk_mul_f32 v[72:73], v[72:73], v[0:1] op_sel_hi:[1,0]
	v_pk_mul_f32 v[70:71], v[70:71], v[0:1] op_sel_hi:[1,0]
	v_pk_mul_f32 v[68:69], v[68:69], v[0:1] op_sel_hi:[1,0]
	v_pk_mul_f32 v[66:67], v[66:67], v[0:1] op_sel_hi:[1,0]
.Lat0_noresc:
	v_sub_f32_e32 v1, v18, v54
	v_sub_f32_e32 v2, v19, v54
	v_sub_f32_e32 v3, v20, v54
	v_sub_f32_e32 v4, v21, v54
	v_sub_f32_e32 v5, v22, v54
	v_sub_f32_e32 v6, v23, v54
	v_sub_f32_e32 v7, v24, v54
	v_sub_f32_e32 v8, v25, v54
	v_exp_f32_e32 v1, v1
	v_exp_f32_e32 v2, v2
	v_exp_f32_e32 v3, v3
	v_exp_f32_e32 v4, v4
	v_exp_f32_e32 v5, v5
	v_exp_f32_e32 v6, v6
	v_exp_f32_e32 v7, v7
	v_exp_f32_e32 v8, v8
	v_sub_f32_e32 v22, v38, v54
	v_sub_f32_e32 v23, v39, v54
	v_sub_f32_e32 v24, v40, v54
	v_sub_f32_e32 v25, v41, v54
	ds_read_b64_tr_b16 v[38:39], v254 offset:128
	ds_read_b64_tr_b16 v[40:41], v254 offset:672
	v_sub_f32_e32 v18, v34, v54
	v_sub_f32_e32 v19, v35, v54
	v_sub_f32_e32 v20, v36, v54
	v_sub_f32_e32 v21, v37, v54
	v_cvt_pk_bf16_f32 v34, v1, v2
	v_cvt_pk_bf16_f32 v35, v3, v4
	v_cvt_pk_bf16_f32 v36, v5, v6
	v_cvt_pk_bf16_f32 v37, v7, v8
	v_sub_f32_e32 v9, v26, v54
	v_sub_f32_e32 v10, v27, v54
	s_waitcnt lgkmcnt(4)
	v_mfma_f32_32x32x16_bf16 v[114:129], v[250:253], v[34:37], v[114:129]
	ds_read_b64_tr_b16 v[250:251], v254 offset:192
	ds_read_b64_tr_b16 v[252:253], v254 offset:736
	v_sub_f32_e32 v11, v28, v54
	v_sub_f32_e32 v12, v29, v54
	v_sub_f32_e32 v13, v30, v54
	v_sub_f32_e32 v14, v31, v54
	v_sub_f32_e32 v15, v32, v54
	v_sub_f32_e32 v17, v33, v54
	s_waitcnt lgkmcnt(4)
	v_mfma_f32_32x32x16_bf16 v[98:113], v[244:247], v[34:37], v[98:113]
	ds_read_b64_tr_b16 v[244:245], v254 offset:4352
	ds_read_b64_tr_b16 v[246:247], v254 offset:4896
	v_exp_f32_e32 v9, v9
	v_exp_f32_e32 v10, v10
	v_exp_f32_e32 v11, v11
	v_exp_f32_e32 v12, v12
	v_exp_f32_e32 v13, v13
	v_exp_f32_e32 v14, v14
	s_waitcnt lgkmcnt(4)
	v_mfma_f32_32x32x16_bf16 v[82:97], v[38:41], v[34:37], v[82:97]
	ds_read_b64_tr_b16 v[38:39], v254 offset:4416
	ds_read_b64_tr_b16 v[40:41], v254 offset:4960
	v_exp_f32_e32 v15, v15
	v_exp_f32_e32 v17, v17
	v_sub_f32_e32 v26, v42, v54
	v_sub_f32_e32 v27, v43, v54
	v_sub_f32_e32 v28, v44, v54
	v_sub_f32_e32 v29, v45, v54
	s_waitcnt lgkmcnt(4)
	v_mfma_f32_32x32x16_bf16 v[66:81], v[250:253], v[34:37], v[66:81]
	ds_read_b64_tr_b16 v[250:251], v254 offset:4480
	ds_read_b64_tr_b16 v[252:253], v254 offset:5024
	v_cvt_pk_bf16_f32 v34, v9, v10
	v_cvt_pk_bf16_f32 v35, v11, v12
	v_cvt_pk_bf16_f32 v36, v13, v14
	v_cvt_pk_bf16_f32 v37, v15, v17
	v_sub_f32_e32 v30, v46, v54
	v_sub_f32_e32 v31, v47, v54
	s_waitcnt lgkmcnt(4)
	v_mfma_f32_32x32x16_bf16 v[114:129], v[244:247], v[34:37], v[114:129]
	ds_read_b64_tr_b16 v[244:245], v254 offset:4544
	ds_read_b64_tr_b16 v[246:247], v254 offset:5088
	v_sub_f32_e32 v32, v48, v54
	v_sub_f32_e32 v33, v49, v54
	v_exp_f32_e32 v18, v18
	v_exp_f32_e32 v19, v19
	v_exp_f32_e32 v20, v20
	v_exp_f32_e32 v21, v21
	s_waitcnt lgkmcnt(4)
	v_mfma_f32_32x32x16_bf16 v[98:113], v[38:41], v[34:37], v[98:113]
	ds_read_b64_tr_b16 v[38:39], v254 offset:8704
	ds_read_b64_tr_b16 v[40:41], v254 offset:9248
	v_exp_f32_e32 v22, v22
	v_exp_f32_e32 v23, v23
	v_exp_f32_e32 v24, v24
	v_exp_f32_e32 v25, v25
	v_exp_f32_e32 v26, v26
	v_exp_f32_e32 v27, v27
	s_waitcnt lgkmcnt(4)
	v_mfma_f32_32x32x16_bf16 v[82:97], v[250:253], v[34:37], v[82:97]
	ds_read_b64_tr_b16 v[250:251], v254 offset:8768
	ds_read_b64_tr_b16 v[252:253], v254 offset:9312
	v_exp_f32_e32 v28, v28
	v_exp_f32_e32 v29, v29
	v_exp_f32_e32 v30, v30
	v_exp_f32_e32 v31, v31
	v_exp_f32_e32 v32, v32
	v_exp_f32_e32 v33, v33
	s_waitcnt lgkmcnt(4)
	v_mfma_f32_32x32x16_bf16 v[66:81], v[244:247], v[34:37], v[66:81]
	ds_read_b64_tr_b16 v[244:245], v254 offset:8832
	ds_read_b64_tr_b16 v[246:247], v254 offset:9376
	s_andn2_b64 vcc, exec, s[84:85]
	s_cbranch_vccnz .Lat0_pvk1off
; __device__ __forceinline__ void attn_unit(const PT& p, LAS unsigned char* lds, int tid, int lane, int wave, int b, int hd, int qb, float lam) {
;     ...
;         for (int sub = 0; sub < 2; ++sub) {
;             const int nact = diag ? min(2, max(0, wq + 1 - 2 * sub)) : 2;
;             if (nact > 0) {
;                 float sl = slope2; asm volatile("" : "+v"(sl));
;                 const float bq = sl * (float)(t * 128 + sub * 64 + 4 * h - q);
;                 const LAS unsigned char* kb0 = kbase + sub * 64 * AK_PITCH; const LAS unsigned char* vb0 = vbase + sub * 64 * AV_PITCH;
;                 f32x16 s[2];
; #pragma unroll
;                 for (int kb = 0; kb < 2; ++kb) {
;                     if (kb < nact) {
;                         const float bk = bq + sl * (float)(32 * kb);
; #pragma unroll
;     ...
;                 for (int kb = 0; kb < 2; ++kb)
; #pragma unroll
;                     for (int i = 0; i < 16; i += 4) { s[kb][i] = fexp2(s[kb][i] - mnew); s[kb][i + 1] = fexp2(s[kb][i + 1] - mnew); s[kb][i + 2] = fexp2(s[kb][i + 2] - mnew); s[kb][i + 3] = fexp2(s[kb][i + 3] - mnew);
;                         rs0 += s[kb][i]; rs1 += s[kb][i + 1]; rs2 += s[kb][i + 2]; rs3 += s[kb][i + 3]; }
;                 lsum = lsum * alpha + ((rs0 + rs1) + (rs2 + rs3));
;                 if (__builtin_amdgcn_ballot_w64(alpha != 1.0f) != 0ull) {
; #pragma unroll
;                     for (int db = 0; db < 4; ++db)
; #pragma unroll
;                         for (int i = 0; i < 16; ++i) oT[db][i] *= alpha;
;                 }
; #pragma unroll
;                 for (int kb = 0; kb < 2; ++kb) if (kb < nact) {
; #pragma unroll
;                     for (int s2 = 0; s2 < 2; ++s2) {
;                         const bf16x8 pf = pack_frag(s[kb], s2);
; #pragma unroll
;                         for (int db = 0; db < 4; ++db) {
;                             const LAS unsigned char* vp = vb0 + (kb * 32 + 16 * s2) * AV_PITCH + db * 64;
;                             const v4i16_t lo = __builtin_amdgcn_ds_read_tr16_b64_v4i16((LAS v4i16_t*)vp), hi = __builtin_amdgcn_ds_read_tr16_b64_v4i16((LAS v4i16_t*)(vp + 8 * AV_PITCH));
;                             const bf16x8 vf = {lo[0], lo[1], lo[2], lo[3], hi[0], hi[1], hi[2], hi[3]};
;                             oT[db] = mfma32(vf, pf, oT[db]);
;                         }
;                     }
;                 }
	v_cvt_pk_bf16_f32 v34, v18, v19
	v_cvt_pk_bf16_f32 v35, v20, v21
	v_cvt_pk_bf16_f32 v36, v22, v23
	v_cvt_pk_bf16_f32 v37, v24, v25
	s_nop 0
	s_waitcnt lgkmcnt(4)
	v_mfma_f32_32x32x16_bf16 v[114:129], v[38:41], v[34:37], v[114:129]
	ds_read_b64_tr_b16 v[38:39], v254 offset:8896
	ds_read_b64_tr_b16 v[40:41], v254 offset:9440
	v_add_f32_e32 v1, v5, v1
	v_add_f32_e32 v2, v6, v2
	v_add_f32_e32 v3, v7, v3
	v_add_f32_e32 v4, v8, v4
	s_waitcnt lgkmcnt(4)
	v_mfma_f32_32x32x16_bf16 v[98:113], v[250:253], v[34:37], v[98:113]
	ds_read_b64_tr_b16 v[250:251], v254 offset:13056
	ds_read_b64_tr_b16 v[252:253], v254 offset:13600
	v_add_f32_e32 v1, v9, v1
	v_add_f32_e32 v2, v10, v2
	v_add_f32_e32 v3, v11, v3
	v_add_f32_e32 v4, v12, v4
	s_waitcnt lgkmcnt(4)
	v_mfma_f32_32x32x16_bf16 v[82:97], v[244:247], v[34:37], v[82:97]
	ds_read_b64_tr_b16 v[244:245], v254 offset:13120
	ds_read_b64_tr_b16 v[246:247], v254 offset:13664
	v_add_f32_e32 v1, v13, v1
	v_add_f32_e32 v2, v14, v2
	v_add_f32_e32 v3, v15, v3
	v_add_f32_e32 v4, v17, v4
	s_waitcnt lgkmcnt(4)
	v_mfma_f32_32x32x16_bf16 v[66:81], v[38:41], v[34:37], v[66:81]
	ds_read_b64_tr_b16 v[38:39], v254 offset:13184
	ds_read_b64_tr_b16 v[40:41], v254 offset:13728
	v_cvt_pk_bf16_f32 v34, v26, v27
	v_cvt_pk_bf16_f32 v35, v28, v29
	v_cvt_pk_bf16_f32 v36, v30, v31
	v_cvt_pk_bf16_f32 v37, v32, v33
	s_nop 0
	s_waitcnt lgkmcnt(4)
	v_mfma_f32_32x32x16_bf16 v[114:129], v[250:253], v[34:37], v[114:129]
	ds_read_b64_tr_b16 v[250:251], v254 offset:13248
	ds_read_b64_tr_b16 v[252:253], v254 offset:13792
	v_add_f32_e32 v1, v18, v1
	v_add_f32_e32 v2, v19, v2
	v_add_f32_e32 v3, v20, v3
	v_add_f32_e32 v4, v21, v4
	v_add_f32_e32 v1, v22, v1
	s_waitcnt lgkmcnt(4)
	v_mfma_f32_32x32x16_bf16 v[98:113], v[244:247], v[34:37], v[98:113]
	v_add_f32_e32 v2, v23, v2
	v_add_f32_e32 v3, v24, v3
	v_add_f32_e32 v4, v25, v4
	v_add_f32_e32 v1, v26, v1
	v_add_f32_e32 v2, v27, v2
	s_waitcnt lgkmcnt(2)
	v_mfma_f32_32x32x16_bf16 v[82:97], v[38:41], v[34:37], v[82:97]
	v_add_f32_e32 v3, v28, v3
	v_add_f32_e32 v4, v29, v4
	v_add_f32_e32 v1, v30, v1
	v_add_f32_e32 v2, v31, v2
	v_add_f32_e32 v3, v32, v3
	v_add_f32_e32 v4, v33, v4
	s_waitcnt lgkmcnt(0)
	v_mfma_f32_32x32x16_bf16 v[66:81], v[250:253], v[34:37], v[66:81]
	v_add_f32_e32 v1, v1, v2
	v_add_f32_e32 v2, v3, v4
	v_add_f32_e32 v53, v1, v2
	v_fmac_f32_e32 v53, v243, v0
	s_branch .Lat0_done
.Lat0_pvk1off:
	s_waitcnt lgkmcnt(0)
	v_add_f32_e32 v1, v5, v1
	v_add_f32_e32 v2, v6, v2
	v_add_f32_e32 v3, v7, v3
	v_add_f32_e32 v4, v8, v4
	v_add_f32_e32 v1, v9, v1
	v_add_f32_e32 v2, v10, v2
	v_add_f32_e32 v3, v11, v3
	v_add_f32_e32 v4, v12, v4
	v_add_f32_e32 v1, v13, v1
	v_add_f32_e32 v2, v14, v2
	v_add_f32_e32 v3, v15, v3
	v_add_f32_e32 v4, v17, v4
	v_add_f32_e32 v1, v18, v1
	v_add_f32_e32 v2, v19, v2
	v_add_f32_e32 v3, v20, v3
	v_add_f32_e32 v4, v21, v4
	v_add_f32_e32 v1, v22, v1
	v_add_f32_e32 v2, v23, v2
	v_add_f32_e32 v3, v24, v3
	v_add_f32_e32 v4, v25, v4
	v_add_f32_e32 v1, v26, v1
	v_add_f32_e32 v2, v27, v2
	v_add_f32_e32 v3, v28, v3
	v_add_f32_e32 v4, v29, v4
	v_add_f32_e32 v1, v30, v1
	v_add_f32_e32 v2, v31, v2
	v_add_f32_e32 v3, v32, v3
	v_add_f32_e32 v4, v33, v4
	v_add_f32_e32 v1, v1, v2
	v_add_f32_e32 v2, v3, v4
	v_add_f32_e32 v53, v1, v2
	v_fmac_f32_e32 v53, v243, v0
.Lat0_done:
	s_and_b64 s[36:37], s[82:83], exec
	s_cselect_b32 s36, 2, s33
	s_cmp_eq_u32 s36, 0
	s_cbranch_scc1 .Lat1_skip
	s_cmp_lg_u32 s36, 1
	s_cselect_b64 s[36:37], -1, 0
	ds_read_b128 v[0:3], v56 offset:17408
	ds_read_b128 v[4:7], v56 offset:17440
	ds_read_b128 v[8:11], v56 offset:17472
	ds_read_b128 v[12:15], v56 offset:17504
	v_add_u32_e32 v50, 64, v242
	v_cvt_f32_i32_e32 v50, v50
	v_mul_f32_e32 v255, v240, v50
	v_mov_b32_e32 v18, v255
	v_add_f32_e32 v19, v240, v255
	v_fma_f32 v20, v240, s62, v255
	v_fma_f32 v21, v240, s63, v255
	v_fma_f32 v22, v240, s64, v255
	v_fma_f32 v23, v240, s65, v255
	v_fma_f32 v24, v240, s66, v255
	v_fma_f32 v25, v240, s67, v255
	v_fma_f32 v26, v240, s68, v255
	v_fma_f32 v27, v240, s69, v255
	v_fma_f32 v28, v240, s70, v255
	v_fma_f32 v29, v240, s71, v255
	v_fma_f32 v30, v240, s72, v255
	v_fma_f32 v31, v240, s73, v255
	v_fma_f32 v32, v240, s74, v255
	v_fma_f32 v33, v240, s75, v255
	s_andn2_b64 vcc, exec, s[36:37]
	s_cbranch_vccnz .Lat1_k1off
	ds_read_b128 v[250:253], v56 offset:26112
	ds_read_b128 v[244:247], v56 offset:26144
	s_waitcnt lgkmcnt(5)
	v_mfma_f32_32x32x16_bf16 v[18:33], v[0:3], v[130:133], v[18:33]
	ds_read_b128 v[0:3], v56 offset:26176
	v_fmac_f32_e32 v255, 0x42000000, v240
	v_mov_b32_e32 v34, v255
	v_add_f32_e32 v35, v240, v255
	v_fma_f32 v36, v240, s62, v255
	v_fma_f32 v37, v240, s63, v255
	v_fma_f32 v38, v240, s64, v255
	s_waitcnt lgkmcnt(5)
	v_mfma_f32_32x32x16_bf16 v[18:33], v[4:7], v[150:153], v[18:33]
	ds_read_b128 v[4:7], v56 offset:26208
	v_fma_f32 v39, v240, s65, v255
	v_fma_f32 v40, v240, s66, v255
	v_fma_f32 v41, v240, s67, v255
	v_fma_f32 v42, v240, s68, v255
	v_fma_f32 v43, v240, s69, v255
	v_fma_f32 v44, v240, s70, v255
	s_waitcnt lgkmcnt(5)
	v_mfma_f32_32x32x16_bf16 v[18:33], v[8:11], v[146:149], v[18:33]
	v_fma_f32 v45, v240, s71, v255
	v_fma_f32 v46, v240, s72, v255
	v_fma_f32 v47, v240, s73, v255
	v_fma_f32 v48, v240, s74, v255
	v_fma_f32 v49, v240, s75, v255
	s_waitcnt lgkmcnt(4)
	v_mfma_f32_32x32x16_bf16 v[18:33], v[12:15], v[142:145], v[18:33]
	s_waitcnt lgkmcnt(3)
	v_mfma_f32_32x32x16_bf16 v[34:49], v[250:253], v[130:133], v[34:49]
	s_waitcnt lgkmcnt(2)
	v_mfma_f32_32x32x16_bf16 v[34:49], v[244:247], v[150:153], v[34:49]
	s_waitcnt lgkmcnt(1)
	v_mfma_f32_32x32x16_bf16 v[34:49], v[0:3], v[146:149], v[34:49]
	s_waitcnt lgkmcnt(0)
	v_mfma_f32_32x32x16_bf16 v[34:49], v[4:7], v[142:145], v[34:49]
	s_branch .Lat1_qkdone

; __device__ __forceinline__ int crow(int r, int h) { return (r & 3) + 8 * (r >> 2) + 4 * h; }
; __device__ __forceinline__ void attn_unit(const PT& p, LAS unsigned char* lds, int tid, int lane, int wave, int b, int hd, int qb, float lam) {
;     ...
;                 if (diag) {
; #pragma unroll
;                     for (int kb = 0; kb < 2; ++kb) if (2 * sub + kb == wq) {
; #pragma unroll
;                         for (int i = 0; i < 16; ++i) if (crow(i, h) > r32) s[kb][i] = -INFINITY; }
;                 }
.Lat1_qkdone:
	s_and_b64 vcc, exec, s[80:81]
	s_cbranch_vccz .Lat1_nodiag
	s_nop 15
	s_andn2_b64 vcc, exec, s[54:55]
	s_cbranch_vccnz .Lat1_m1
	v_cndmask_b32_e64 v18, v18, v16, s[0:1]
	v_cndmask_b32_e64 v19, v16, v19, s[4:5]
	v_cndmask_b32_e64 v20, v20, v16, s[6:7]
	v_cndmask_b32_e64 v21, v21, v16, s[8:9]
	v_cndmask_b32_e64 v22, v22, v16, s[10:11]
	v_cndmask_b32_e64 v23, v23, v16, s[12:13]
	v_cndmask_b32_e64 v24, v24, v16, s[14:15]
	v_cndmask_b32_e64 v25, v25, v16, s[16:17]
	v_cndmask_b32_e64 v26, v26, v16, s[18:19]
	v_cndmask_b32_e64 v27, v27, v16, s[20:21]
	v_cndmask_b32_e64 v28, v28, v16, s[22:23]
	v_cndmask_b32_e64 v29, v29, v16, s[24:25]
	v_cndmask_b32_e64 v30, v30, v16, s[26:27]
	v_cndmask_b32_e64 v31, v31, v16, s[28:29]
	v_cndmask_b32_e64 v32, v32, v16, s[30:31]
	v_cndmask_b32_e64 v33, v33, v16, s[34:35]

; #define LAS __attribute__((address_space(3)))
; __device__ __forceinline__ float fexp2(float x) { return __builtin_amdgcn_exp2f(x); }
; __device__ __forceinline__ float max3f(float a, float b, float c) { return fmaxf(fmaxf(a, b), c); }
; __device__ __forceinline__ void attn_unit(const PT& p, LAS unsigned char* lds, int tid, int lane, int wave, int b, int hd, int qb, float lam) {
;     ...
;                 float mx = -INFINITY;
; #pragma unroll
;                 for (int kb = 0; kb < 2; ++kb)
; #pragma unroll
;                     for (int i = 0; i < 16; i += 2) mx = max3f(mx, s[kb][i], s[kb][i + 1]);
;                 mx = fmaxf(mx, __shfl_xor(mx, 32));
;                 const float mnew = fmaxf(mrun, mx), alpha = fexp2(mrun - mnew); mrun = mnew;
;                 float rs0 = 0.f, rs1 = 0.f, rs2 = 0.f, rs3 = 0.f;
; #pragma unroll
;                 for (int kb = 0; kb < 2; ++kb)
; #pragma unroll
;                     for (int i = 0; i < 16; i += 4) { s[kb][i] = fexp2(s[kb][i] - mnew); s[kb][i + 1] = fexp2(s[kb][i + 1] - mnew); s[kb][i + 2] = fexp2(s[kb][i + 2] - mnew); s[kb][i + 3] = fexp2(s[kb][i + 3] - mnew);
;                         rs0 += s[kb][i]; rs1 += s[kb][i + 1]; rs2 += s[kb][i + 2]; rs3 += s[kb][i + 3]; }
;                 lsum = lsum * alpha + ((rs0 + rs1) + (rs2 + rs3));
;                 if (__builtin_amdgcn_ballot_w64(alpha != 1.0f) != 0ull) {
; #pragma unroll
;                     for (int db = 0; db < 4; ++db)
; #pragma unroll
;                         for (int i = 0; i < 16; ++i) oT[db][i] *= alpha;
;                 }
; #pragma unroll
;                 for (int kb = 0; kb < 2; ++kb) if (kb < nact) {
; #pragma unroll
;                     for (int s2 = 0; s2 < 2; ++s2) {
;                         const bf16x8 pf = pack_frag(s[kb], s2);
; #pragma unroll
;                         for (int db = 0; db < 4; ++db) {
;                             const LAS unsigned char* vp = vb0 + (kb * 32 + 16 * s2) * AV_PITCH + db * 64;
;                             const v4i16_t lo = __builtin_amdgcn_ds_read_tr16_b64_v4i16((LAS v4i16_t*)vp), hi = __builtin_amdgcn_ds_read_tr16_b64_v4i16((LAS v4i16_t*)(vp + 8 * AV_PITCH));
;                             const bf16x8 vf = {lo[0], lo[1], lo[2], lo[3], hi[0], hi[1], hi[2], hi[3]};
;                             oT[db] = mfma32(vf, pf, oT[db]);
;                         }
;                     }
;                 }
.Lat1_nodiag:
	ds_read_b64_tr_b16 v[250:251], v254 offset:17408
	ds_read_b64_tr_b16 v[252:253], v254 offset:17952
	ds_read_b64_tr_b16 v[244:245], v254 offset:17472
	ds_read_b64_tr_b16 v[246:247], v254 offset:18016
	s_nop 1
	v_max3_f32 v0, v18, s89, v19
	v_max3_f32 v0, v0, v20, v21
	v_max3_f32 v0, v0, v22, v23
	v_max3_f32 v0, v0, v24, v25
	v_max3_f32 v0, v0, v26, v27
	v_max3_f32 v0, v0, v28, v29
	v_max3_f32 v0, v0, v30, v31
	v_max3_f32 v0, v0, v32, v33
	v_max3_f32 v0, v0, v34, v35
	v_max3_f32 v0, v0, v36, v37
	v_max3_f32 v0, v0, v38, v39
	v_max3_f32 v0, v0, v40, v41
	v_max3_f32 v0, v0, v42, v43
	v_max3_f32 v0, v0, v44, v45
	v_max3_f32 v0, v0, v46, v47
	v_max3_f32 v0, v0, v48, v49
	v_mov_b32_e32 v1, v0
	s_nop 1
	v_permlane32_swap_b32_e32 v0, v1
	v_max3_f32 v248, v54, v0, v1
	v_sub_f32_e32 v0, v54, v248
	v_exp_f32_e32 v0, v0
	s_nop 0
	v_cmp_neq_f32_e32 vcc, 1.0, v0
	s_cbranch_vccz .Lat1_noresc
	v_pk_mul_f32 v[128:129], v[128:129], v[0:1] op_sel_hi:[1,0]
	v_pk_mul_f32 v[126:127], v[126:127], v[0:1] op_sel_hi:[1,0]
	v_pk_mul_f32 v[124:125], v[124:125], v[0:1] op_sel_hi:[1,0]
	v_pk_mul_f32 v[122:123], v[122:123], v[0:1] op_sel_hi:[1,0]
	v_pk_mul_f32 v[120:121], v[120:121], v[0:1] op_sel_hi:[1,0]
	v_pk_mul_f32 v[118:119], v[118:119], v[0:1] op_sel_hi:[1,0]
	v_pk_mul_f32 v[116:117], v[116:117], v[0:1] op_sel_hi:[1,0]
	v_pk_mul_f32 v[114:115], v[114:115], v[0:1] op_sel_hi:[1,0]
	v_pk_mul_f32 v[112:113], v[112:113], v[0:1] op_sel_hi:[1,0]
	v_pk_mul_f32 v[110:111], v[110:111], v[0:1] op_sel_hi:[1,0]
	v_pk_mul_f32 v[108:109], v[108:109], v[0:1] op_sel_hi:[1,0]
	v_pk_mul_f32 v[106:107], v[106:107], v[0:1] op_sel_hi:[1,0]
	v_pk_mul_f32 v[104:105], v[104:105], v[0:1] op_sel_hi:[1,0]
	v_pk_mul_f32 v[102:103], v[102:103], v[0:1] op_sel_hi:[1,0]
	v_pk_mul_f32 v[100:101], v[100:101], v[0:1] op_sel_hi:[1,0]
	v_pk_mul_f32 v[98:99], v[98:99], v[0:1] op_sel_hi:[1,0]
	v_pk_mul_f32 v[96:97], v[96:97], v[0:1] op_sel_hi:[1,0]
	v_pk_mul_f32 v[94:95], v[94:95], v[0:1] op_sel_hi:[1,0]
	v_pk_mul_f32 v[92:93], v[92:93], v[0:1] op_sel_hi:[1,0]
	v_pk_mul_f32 v[90:91], v[90:91], v[0:1] op_sel_hi:[1,0]
	v_pk_mul_f32 v[88:89], v[88:89], v[0:1] op_sel_hi:[1,0]
	v_pk_mul_f32 v[86:87], v[86:87], v[0:1] op_sel_hi:[1,0]
	v_pk_mul_f32 v[84:85], v[84:85], v[0:1] op_sel_hi:[1,0]
	v_pk_mul_f32 v[82:83], v[82:83], v[0:1] op_sel_hi:[1,0]
	v_pk_mul_f32 v[80:81], v[80:81], v[0:1] op_sel_hi:[1,0]
	v_pk_mul_f32 v[78:79], v[78:79], v[0:1] op_sel_hi:[1,0]
	v_pk_mul_f32 v[76:77], v[76:77], v[0:1] op_sel_hi:[1,0]
	v_pk_mul_f32 v[74:75], v[74:75], v[0:1] op_sel_hi:[1,0]
	v_pk_mul_f32 v[72:73], v[72:73], v[0:1] op_sel_hi:[1,0]
	v_pk_mul_f32 v[70:71], v[70:71], v[0:1] op_sel_hi:[1,0]
	v_pk_mul_f32 v[68:69], v[68:69], v[0:1] op_sel_hi:[1,0]
	v_pk_mul_f32 v[66:67], v[66:67], v[0:1] op_sel_hi:[1,0]
.Lat1_noresc:
	v_sub_f32_e32 v1, v18, v248
	v_sub_f32_e32 v2, v19, v248
	v_sub_f32_e32 v3, v20, v248
	v_sub_f32_e32 v4, v21, v248
	v_sub_f32_e32 v5, v22, v248
	v_sub_f32_e32 v6, v23, v248
	v_sub_f32_e32 v7, v24, v248
	v_sub_f32_e32 v8, v25, v248
	v_exp_f32_e32 v1, v1
	v_exp_f32_e32 v2, v2
	v_exp_f32_e32 v3, v3
	v_exp_f32_e32 v4, v4
	v_exp_f32_e32 v5, v5
	v_exp_f32_e32 v6, v6
	v_exp_f32_e32 v7, v7
	v_exp_f32_e32 v8, v8
	v_sub_f32_e32 v22, v38, v248
	v_sub_f32_e32 v23, v39, v248
	v_sub_f32_e32 v24, v40, v248
	v_sub_f32_e32 v25, v41, v248
	ds_read_b64_tr_b16 v[38:39], v254 offset:17536
	ds_read_b64_tr_b16 v[40:41], v254 offset:18080
	v_sub_f32_e32 v18, v34, v248
	v_sub_f32_e32 v19, v35, v248
	v_sub_f32_e32 v20, v36, v248
	v_sub_f32_e32 v21, v37, v248
	v_cvt_pk_bf16_f32 v34, v1, v2
	v_cvt_pk_bf16_f32 v35, v3, v4
	v_cvt_pk_bf16_f32 v36, v5, v6
	v_cvt_pk_bf16_f32 v37, v7, v8
	v_sub_f32_e32 v9, v26, v248
	v_sub_f32_e32 v10, v27, v248
	s_waitcnt lgkmcnt(4)
	v_mfma_f32_32x32x16_bf16 v[114:129], v[250:253], v[34:37], v[114:129]
	ds_read_b64_tr_b16 v[250:251], v254 offset:17600
	ds_read_b64_tr_b16 v[252:253], v254 offset:18144
	v_sub_f32_e32 v11, v28, v248
	v_sub_f32_e32 v12, v29, v248
	v_sub_f32_e32 v13, v30, v248
	v_sub_f32_e32 v14, v31, v248
	v_sub_f32_e32 v15, v32, v248
	v_sub_f32_e32 v17, v33, v248
	s_waitcnt lgkmcnt(4)
	v_mfma_f32_32x32x16_bf16 v[98:113], v[244:247], v[34:37], v[98:113]
	ds_read_b64_tr_b16 v[244:245], v254 offset:21760
	ds_read_b64_tr_b16 v[246:247], v254 offset:22304
	v_exp_f32_e32 v9, v9
	v_exp_f32_e32 v10, v10
	v_exp_f32_e32 v11, v11
	v_exp_f32_e32 v12, v12
	v_exp_f32_e32 v13, v13
	v_exp_f32_e32 v14, v14
	s_waitcnt lgkmcnt(4)
	v_mfma_f32_32x32x16_bf16 v[82:97], v[38:41], v[34:37], v[82:97]
	ds_read_b64_tr_b16 v[38:39], v254 offset:21824
	ds_read_b64_tr_b16 v[40:41], v254 offset:22368
	v_exp_f32_e32 v15, v15
	v_exp_f32_e32 v17, v17
	v_sub_f32_e32 v26, v42, v248
	v_sub_f32_e32 v27, v43, v248
	v_sub_f32_e32 v28, v44, v248
	v_sub_f32_e32 v29, v45, v248
	s_waitcnt lgkmcnt(4)
	v_mfma_f32_32x32x16_bf16 v[66:81], v[250:253], v[34:37], v[66:81]
	ds_read_b64_tr_b16 v[250:251], v254 offset:21888
	ds_read_b64_tr_b16 v[252:253], v254 offset:22432
	v_cvt_pk_bf16_f32 v34, v9, v10
	v_cvt_pk_bf16_f32 v35, v11, v12
	v_cvt_pk_bf16_f32 v36, v13, v14
	v_cvt_pk_bf16_f32 v37, v15, v17
	v_sub_f32_e32 v30, v46, v248
	v_sub_f32_e32 v31, v47, v248
	s_waitcnt lgkmcnt(4)
	v_mfma_f32_32x32x16_bf16 v[114:129], v[244:247], v[34:37], v[114:129]
	ds_read_b64_tr_b16 v[244:245], v254 offset:21952
	ds_read_b64_tr_b16 v[246:247], v254 offset:22496
	v_sub_f32_e32 v32, v48, v248
	v_sub_f32_e32 v33, v49, v248
	v_exp_f32_e32 v18, v18
	v_exp_f32_e32 v19, v19
	v_exp_f32_e32 v20, v20
	v_exp_f32_e32 v21, v21
	s_waitcnt lgkmcnt(4)
	v_mfma_f32_32x32x16_bf16 v[98:113], v[38:41], v[34:37], v[98:113]
	ds_read_b64_tr_b16 v[38:39], v254 offset:26112
	ds_read_b64_tr_b16 v[40:41], v254 offset:26656
	v_exp_f32_e32 v22, v22
	v_exp_f32_e32 v23, v23
	v_exp_f32_e32 v24, v24
	v_exp_f32_e32 v25, v25
	v_exp_f32_e32 v26, v26
	v_exp_f32_e32 v27, v27
	s_waitcnt lgkmcnt(4)
	v_mfma_f32_32x32x16_bf16 v[82:97], v[250:253], v[34:37], v[82:97]
	ds_read_b64_tr_b16 v[250:251], v254 offset:26176
	ds_read_b64_tr_b16 v[252:253], v254 offset:26720
	v_exp_f32_e32 v28, v28
	v_exp_f32_e32 v29, v29
	v_exp_f32_e32 v30, v30
	v_exp_f32_e32 v31, v31
	v_exp_f32_e32 v32, v32
	v_exp_f32_e32 v33, v33
	s_waitcnt lgkmcnt(4)
	v_mfma_f32_32x32x16_bf16 v[66:81], v[244:247], v[34:37], v[66:81]
	ds_read_b64_tr_b16 v[244:245], v254 offset:26240
	ds_read_b64_tr_b16 v[246:247], v254 offset:26784
	s_andn2_b64 vcc, exec, s[36:37]
	s_cbranch_vccnz .Lat1_pvk1off
; #define LAS __attribute__((address_space(3)))
; __device__ __forceinline__ f32x16 mfma32(bf16x8 a, bf16x8 b, f32x16 c) { return __builtin_amdgcn_mfma_f32_32x32x16_bf16(a, b, c, 0, 0, 0); }
; #define STAGE_WRITE(stg) do { \
;         _Pragma("unroll") for (int i_ = 0; i_ < 4; ++i_) { const int pid_ = tid + 512 * i_, row_ = pid_ >> 4, c16_ = pid_ & 15; \
;             *(LAS u32x4*)(lds + (stg) * A_STAGE + A_KOFF + row_ * AK_PITCH + 16 * c16_) = preK[i_]; *(LAS u32x4*)(lds + (stg) * A_STAGE + A_VOFF + row_ * AV_PITCH + 16 * c16_) = preV[i_]; } \
;     } while (0)
; __device__ __forceinline__ void attn_unit(const PT& p, LAS unsigned char* lds, int tid, int lane, int wave, int b, int hd, int qb, float lam) {
;     ...
;                 for (int kb = 0; kb < 2; ++kb) if (kb < nact) {
; #pragma unroll
;                     for (int s2 = 0; s2 < 2; ++s2) {
;                         const bf16x8 pf = pack_frag(s[kb], s2);
; #pragma unroll
;                         for (int db = 0; db < 4; ++db) {
;                             const LAS unsigned char* vp = vb0 + (kb * 32 + 16 * s2) * AV_PITCH + db * 64;
;                             const v4i16_t lo = __builtin_amdgcn_ds_read_tr16_b64_v4i16((LAS v4i16_t*)vp), hi = __builtin_amdgcn_ds_read_tr16_b64_v4i16((LAS v4i16_t*)(vp + 8 * AV_PITCH));
;                             const bf16x8 vf = {lo[0], lo[1], lo[2], lo[3], hi[0], hi[1], hi[2], hi[3]};
;                             oT[db] = mfma32(vf, pf, oT[db]);
;                         }
;                     }
;                 }
;             }
;         }
;         if (t + 1 < ntiles) STAGE_WRITE(stg ^ 1);
;         __syncthreads();
	v_cvt_pk_bf16_f32 v34, v18, v19
	v_cvt_pk_bf16_f32 v35, v20, v21
	v_cvt_pk_bf16_f32 v36, v22, v23
	v_cvt_pk_bf16_f32 v37, v24, v25
	s_nop 0
	s_waitcnt lgkmcnt(4)
	v_mfma_f32_32x32x16_bf16 v[114:129], v[38:41], v[34:37], v[114:129]
	ds_read_b64_tr_b16 v[38:39], v254 offset:26304
	ds_read_b64_tr_b16 v[40:41], v254 offset:26848
	v_add_f32_e32 v1, v5, v1
	v_add_f32_e32 v2, v6, v2
	v_add_f32_e32 v3, v7, v3
	v_add_f32_e32 v4, v8, v4
	s_waitcnt lgkmcnt(4)
	v_mfma_f32_32x32x16_bf16 v[98:113], v[250:253], v[34:37], v[98:113]
	ds_read_b64_tr_b16 v[250:251], v254 offset:30464
	ds_read_b64_tr_b16 v[252:253], v254 offset:31008
	v_add_f32_e32 v1, v9, v1
	v_add_f32_e32 v2, v10, v2
	v_add_f32_e32 v3, v11, v3
	v_add_f32_e32 v4, v12, v4
	s_waitcnt lgkmcnt(4)
	v_mfma_f32_32x32x16_bf16 v[82:97], v[244:247], v[34:37], v[82:97]
	ds_read_b64_tr_b16 v[244:245], v254 offset:30528
	ds_read_b64_tr_b16 v[246:247], v254 offset:31072
	v_add_f32_e32 v1, v13, v1
	v_add_f32_e32 v2, v14, v2
	v_add_f32_e32 v3, v15, v3
	v_add_f32_e32 v4, v17, v4
	s_waitcnt lgkmcnt(4)
	v_mfma_f32_32x32x16_bf16 v[66:81], v[38:41], v[34:37], v[66:81]
	ds_read_b64_tr_b16 v[38:39], v254 offset:30592
	ds_read_b64_tr_b16 v[40:41], v254 offset:31136
	v_cvt_pk_bf16_f32 v34, v26, v27
	v_cvt_pk_bf16_f32 v35, v28, v29
	v_cvt_pk_bf16_f32 v36, v30, v31
	v_cvt_pk_bf16_f32 v37, v32, v33
	s_nop 0
	s_waitcnt lgkmcnt(4)
	v_mfma_f32_32x32x16_bf16 v[114:129], v[250:253], v[34:37], v[114:129]
	ds_read_b64_tr_b16 v[250:251], v254 offset:30656
	ds_read_b64_tr_b16 v[252:253], v254 offset:31200
	v_add_f32_e32 v1, v18, v1
	v_add_f32_e32 v2, v19, v2
	v_add_f32_e32 v3, v20, v3
	v_add_f32_e32 v4, v21, v4
	v_add_f32_e32 v1, v22, v1
	s_waitcnt lgkmcnt(4)
	v_mfma_f32_32x32x16_bf16 v[98:113], v[244:247], v[34:37], v[98:113]
	v_add_f32_e32 v2, v23, v2
	v_add_f32_e32 v3, v24, v3
	v_add_f32_e32 v4, v25, v4
	v_add_f32_e32 v1, v26, v1
	v_add_f32_e32 v2, v27, v2
	s_waitcnt lgkmcnt(2)
	v_mfma_f32_32x32x16_bf16 v[82:97], v[38:41], v[34:37], v[82:97]
	v_add_f32_e32 v3, v28, v3
	v_add_f32_e32 v4, v29, v4
	v_add_f32_e32 v1, v30, v1
	v_add_f32_e32 v2, v31, v2
	v_add_f32_e32 v3, v32, v3
	v_add_f32_e32 v4, v33, v4
	s_waitcnt lgkmcnt(0)
	v_mfma_f32_32x32x16_bf16 v[66:81], v[250:253], v[34:37], v[66:81]
	v_add_f32_e32 v1, v1, v2
	v_add_f32_e32 v2, v3, v4
	v_add_f32_e32 v243, v1, v2
	v_fmac_f32_e32 v243, v53, v0
	s_branch .Lat1_done
.Lat1_pvk1off:
	s_waitcnt lgkmcnt(0)
	v_add_f32_e32 v1, v5, v1
	v_add_f32_e32 v2, v6, v2
	v_add_f32_e32 v3, v7, v3
	v_add_f32_e32 v4, v8, v4
	v_add_f32_e32 v1, v9, v1
	v_add_f32_e32 v2, v10, v2
	v_add_f32_e32 v3, v11, v3
	v_add_f32_e32 v4, v12, v4
	v_add_f32_e32 v1, v13, v1
	v_add_f32_e32 v2, v14, v2
	v_add_f32_e32 v3, v15, v3
	v_add_f32_e32 v4, v17, v4
	v_add_f32_e32 v1, v18, v1
	v_add_f32_e32 v2, v19, v2
	v_add_f32_e32 v3, v20, v3
	v_add_f32_e32 v4, v21, v4
	v_add_f32_e32 v1, v22, v1
	v_add_f32_e32 v2, v23, v2
	v_add_f32_e32 v3, v24, v3
	v_add_f32_e32 v4, v25, v4
	v_add_f32_e32 v1, v26, v1
	v_add_f32_e32 v2, v27, v2
	v_add_f32_e32 v3, v28, v3
	v_add_f32_e32 v4, v29, v4
	v_add_f32_e32 v1, v30, v1
	v_add_f32_e32 v2, v31, v2
	v_add_f32_e32 v3, v32, v3
	v_add_f32_e32 v4, v33, v4
	v_add_f32_e32 v1, v1, v2
	v_add_f32_e32 v2, v3, v4
	v_add_f32_e32 v243, v1, v2
	v_fmac_f32_e32 v243, v53, v0
	s_branch .Lat1_done
.Lat1_skip:
	v_mov_b32_e32 v248, v54
	v_mov_b32_e32 v243, v53
.Lat1_done:
	s_and_b64 vcc, exec, s[78:79]
	s_cbranch_vccz .LBB0_1075
.LBB0_1104:
	s_xor_b32 s36, s87, 1
	s_mul_i32 s36, s36, 0x11000
	v_add_u32_e32 v0, s36, v206
	v_add_u32_e32 v1, v0, v207
	s_waitcnt vmcnt(7)
	ds_write_b128 v1, v[134:137]
	s_waitcnt vmcnt(6)
	v_bfe_u32 v2, v196, 4, 2
	v_bfe_u32 v3, v196, 6, 2
	v_sub_u32_e32 v2, v2, v3
	v_mul_i32_i24_e32 v2, 0x330, v2
	v_add_u32_e32 v3, v2, v1
	ds_write_b128 v3, v[138:141] offset:34816
	v_add_u32_e32 v1, v0, v208
	s_waitcnt vmcnt(5)
	ds_write_b128 v1, v[154:157]
	s_waitcnt vmcnt(4)
	v_add_u32_e32 v3, v2, v1
	ds_write_b128 v3, v[158:161] offset:34816
	v_add_u32_e32 v1, v0, v209
	v_add_u32_e32 v0, v0, v210
	s_waitcnt vmcnt(3)
	ds_write_b128 v1, v[162:165]
	s_waitcnt vmcnt(2)
	v_add_u32_e32 v3, v2, v1
	ds_write_b128 v3, v[166:169] offset:34816
	s_waitcnt vmcnt(1)
	ds_write_b128 v0, v[170:173]
	s_waitcnt vmcnt(0)
	v_add_u32_e32 v3, v2, v0
	ds_write_b128 v3, v[174:177] offset:34816
	s_branch .LBB0_1075

; __global__ void __launch_bounds__(512) fwd_megakernel(Params pa) {
	.amdhsa_kernel _Z14fwd_megakernel6Params
		.amdhsa_group_segment_fixed_size 0
		.amdhsa_private_segment_fixed_size 0
		.amdhsa_kernarg_size 456
		.amdhsa_user_sgpr_count 2
		.amdhsa_user_sgpr_dispatch_ptr 0
		.amdhsa_user_sgpr_queue_ptr 0
		.amdhsa_user_sgpr_kernarg_segment_ptr 1
		.amdhsa_user_sgpr_dispatch_id 0
		.amdhsa_user_sgpr_kernarg_preload_length 0
		.amdhsa_user_sgpr_kernarg_preload_offset 0
		.amdhsa_user_sgpr_private_segment_size 0
		.amdhsa_uses_dynamic_stack 0
		.amdhsa_enable_private_segment 0
		.amdhsa_system_sgpr_workgroup_id_x 1
		.amdhsa_system_sgpr_workgroup_id_y 0
		.amdhsa_system_sgpr_workgroup_id_z 0
		.amdhsa_system_sgpr_workgroup_info 0
		.amdhsa_system_vgpr_workitem_id 2
		.amdhsa_next_free_vgpr 256
		.amdhsa_next_free_sgpr 100
		.amdhsa_accum_offset 256
		.amdhsa_reserve_vcc 1
		.amdhsa_float_round_mode_32 0
		.amdhsa_float_round_mode_16_64 0
		.amdhsa_float_denorm_mode_32 3
		.amdhsa_float_denorm_mode_16_64 3
		.amdhsa_dx10_clamp 1
		.amdhsa_ieee_mode 1
		.amdhsa_fp16_overflow 0
		.amdhsa_tg_split 0
		.amdhsa_exception_fp_ieee_invalid_op 0
		.amdhsa_exception_fp_denorm_src 0
		.amdhsa_exception_fp_ieee_div_zero 0
		.amdhsa_exception_fp_ieee_overflow 0
		.amdhsa_exception_fp_ieee_underflow 0
		.amdhsa_exception_fp_ieee_inexact 0
		.amdhsa_exception_int_div_zero 0
	.end_amdhsa_kernel

; __global__ void __launch_bounds__(512) fwd_megakernel(Params pa) {
amdhsa.kernels:
  - .agpr_count:     0
    .args:
      - .offset:         0
        .size:           200
        .value_kind:     by_value
      - .offset:         200
        .size:           4
        .value_kind:     hidden_block_count_x
      - .offset:         204
        .size:           4
        .value_kind:     hidden_block_count_y
      - .offset:         208
        .size:           4
        .value_kind:     hidden_block_count_z
      - .offset:         212
        .size:           2
        .value_kind:     hidden_group_size_x
      - .offset:         214
        .size:           2
        .value_kind:     hidden_group_size_y
      - .offset:         216
        .size:           2
        .value_kind:     hidden_group_size_z
      - .offset:         218
        .size:           2
        .value_kind:     hidden_remainder_x
      - .offset:         220
        .size:           2
        .value_kind:     hidden_remainder_y
      - .offset:         222
        .size:           2
        .value_kind:     hidden_remainder_z
      - .offset:         240
        .size:           8
        .value_kind:     hidden_global_offset_x
      - .offset:         248
        .size:           8
        .value_kind:     hidden_global_offset_y
      - .offset:         256
        .size:           8
        .value_kind:     hidden_global_offset_z
      - .offset:         264
        .size:           2
        .value_kind:     hidden_grid_dims
      - .offset:         288
        .size:           8
        .value_kind:     hidden_multigrid_sync_arg
      - .offset:         320
        .size:           4
        .value_kind:     hidden_dynamic_lds_size
    .group_segment_fixed_size: 0
    .kernarg_segment_align: 8
    .kernarg_segment_size: 456
    .language:       OpenCL C
    .language_version:
      - 2
      - 0
    .max_flat_workgroup_size: 512
    .name:           _Z14fwd_megakernel6Params
    .private_segment_fixed_size: 0
    .sgpr_count:     106
    .sgpr_spill_count: 226
    .symbol:         _Z14fwd_megakernel6Params.kd
    .uniform_work_group_size: 1
    .uses_dynamic_stack: false
    .vgpr_count:     256
    .vgpr_spill_count: 0
    .wavefront_size: 64
